# attention unit epilogues: gate/subln loads hoisted (one wait); NA latent QK^T: all 8 K fragments issued up front with counted lgkmcnt
# baseline (speedup 1.0000x reference)
; template <int KW, int DV, bool NA> ...
;     ...
;         for (int d0 = 0; d0 < 4; ++d0) {
;             const bf16x8 a0 = *(const bf16x8*)(Kt + q32 * KSTR + (kcoff + 16 * d0 + 8 * hi) * 2);
;             const bf16x8 a1 = *(const bf16x8*)(Kt + (32 + q32) * KSTR + (kcoff + 16 * d0 + 8 * hi) * 2);
;             if (d0 == 0) { p0 = __builtin_amdgcn_mfma_f32_32x32x16_bf16(a0, qf[0], negm, 0, 0, 0); p1 = __builtin_amdgcn_mfma_f32_32x32x16_bf16(a1, qf[0], negm, 0, 0, 0); }
;             else { p0 = __builtin_amdgcn_mfma_f32_32x32x16_bf16(a0, qf[d0], p0, 0, 0, 0); p1 = __builtin_amdgcn_mfma_f32_32x32x16_bf16(a1, qf[d0], p1, 0, 0, 0); }
;         }
;         if (NA && i < n1) {
;             const int kr = na_row0 + i, dr = kr - na_r + 7;
;             const int cs = min(max(na_c - 8, 0), 48);
;             const float* rb = rpbs + dr * 31 - na_c + 15;
; #pragma unroll
;             for (int r = 0; r < 16; ++r) {
;                 const int kc0 = (r & 3) + 8 * (r >> 2) + 4 * hi, kc1 = kc0 + 32;
;                 const bool ok0 = (kc0 >= cs) && (kc0 < cs + 16), ok1 = (kc1 >= cs) && (kc1 < cs + 16);
;                 p0[r] = ok0 ? p0[r] + rb[kc0] : -1e30f;
;                 p1[r] = ok1 ? p1[r] + rb[kc1] : -1e30f;
;             }
;         }
.LBB0_430:
	s_or_b64 exec, exec, s[74:75]
	s_add_i32 s7, s2, -4
	v_cmp_ge_i32_e64 s[82:83], s7, v163
	v_cmp_lt_i32_e64 s[74:75], s7, v163
	s_and_saveexec_b64 s[26:27], s[74:75]
	v_cmp_ge_i32_e64 s[0:1], s7, v164
	v_cmp_lt_i32_e64 s[78:79], s7, v165
	s_and_b64 s[0:1], s[0:1], s[78:79]
	s_andn2_b64 s[78:79], s[82:83], exec
	s_and_b64 s[0:1], s[0:1], exec
	s_or_b64 s[82:83], s[78:79], s[0:1]
	s_or_b64 exec, exec, s[26:27]
	s_and_saveexec_b64 s[78:79], s[82:83]
	s_cbranch_execz .LBB0_504
	s_movk_i32 s0, 0x5400
	v_mul_lo_u32 v0, v174, s0
	v_add_u32_e32 v0, 0, v0
	v_add3_u32 v86, v0, v166, v167
	ds_read_b128 v[50:53], v86
	ds_read_b128 v[82:85], v86 offset:4608
	ds_read_b128 v[88:91], v86 offset:32
	ds_read_b128 v[92:95], v86 offset:4640
	ds_read_b128 v[96:99], v86 offset:64
	ds_read_b128 v[100:103], v86 offset:4672
	ds_read_b128 v[104:107], v86 offset:96
	ds_read_b128 v[108:111], v86 offset:4704
	s_waitcnt lgkmcnt(7)
	v_mfma_f32_32x32x16_bf16 v[66:81], v[50:53], v[114:117], v[34:49]
	s_waitcnt lgkmcnt(6)
	v_mfma_f32_32x32x16_bf16 v[50:65], v[82:85], v[114:117], v[34:49]
	s_waitcnt lgkmcnt(5)
	v_mfma_f32_32x32x16_bf16 v[66:81], v[88:91], v[118:121], v[66:81]
	s_waitcnt lgkmcnt(4)
	v_mfma_f32_32x32x16_bf16 v[50:65], v[92:95], v[118:121], v[50:65]
	s_waitcnt lgkmcnt(3)
	v_mfma_f32_32x32x16_bf16 v[66:81], v[96:99], v[122:125], v[66:81]
	s_waitcnt lgkmcnt(2)
	v_mfma_f32_32x32x16_bf16 v[50:65], v[100:103], v[122:125], v[50:65]
	s_waitcnt lgkmcnt(1)
	v_mfma_f32_32x32x16_bf16 v[66:81], v[104:107], v[126:129], v[66:81]
	s_waitcnt lgkmcnt(0)
	v_mfma_f32_32x32x16_bf16 v[50:65], v[108:111], v[126:129], v[50:65]
	s_and_saveexec_b64 s[0:1], s[74:75]
	s_cbranch_execz .LBB0_499
	ds_read_b32 v98, v172
	ds_read_b32 v82, v172 offset:128
	ds_read_b32 v99, v172 offset:4
	ds_read_b32 v83, v172 offset:132
	ds_read_b32 v100, v172 offset:8
	ds_read_b32 v84, v172 offset:136
	ds_read_b32 v101, v172 offset:12
	ds_read_b32 v85, v172 offset:140
	ds_read_b32 v102, v172 offset:32
	ds_read_b32 v86, v172 offset:160
	ds_read_b32 v103, v172 offset:36
	ds_read_b32 v87, v172 offset:164
	ds_read_b32 v104, v172 offset:40
	ds_read_b32 v88, v172 offset:168
	ds_read_b32 v105, v172 offset:44
	ds_read_b32 v89, v172 offset:172
	ds_read_b32 v106, v172 offset:64
	ds_read_b32 v90, v172 offset:192
	ds_read_b32 v107, v172 offset:68
	ds_read_b32 v91, v172 offset:196
	ds_read_b32 v108, v172 offset:72
	ds_read_b32 v92, v172 offset:200
	ds_read_b32 v109, v172 offset:76
	ds_read_b32 v93, v172 offset:204
	ds_read_b32 v110, v172 offset:96
	ds_read_b32 v94, v172 offset:224
	ds_read_b32 v111, v172 offset:100
	ds_read_b32 v95, v172 offset:228
	ds_read_b32 v112, v172 offset:104
	ds_read_b32 v96, v172 offset:232
	ds_read_b32 v113, v172 offset:108
	ds_read_b32 v97, v172 offset:236
	s_waitcnt lgkmcnt(0)
	v_add_f32_e32 v66, v66, v98
	v_add_f32_e32 v50, v50, v82
	v_add_f32_e32 v67, v67, v99
	v_add_f32_e32 v51, v51, v83
	v_add_f32_e32 v68, v68, v100
	v_add_f32_e32 v52, v52, v84
	v_add_f32_e32 v69, v69, v101
	v_add_f32_e32 v53, v53, v85
	v_add_f32_e32 v70, v70, v102
	v_add_f32_e32 v54, v54, v86
	v_add_f32_e32 v71, v71, v103
	v_add_f32_e32 v55, v55, v87
	v_add_f32_e32 v72, v72, v104
	v_add_f32_e32 v56, v56, v88
	v_add_f32_e32 v73, v73, v105
	v_add_f32_e32 v57, v57, v89
	v_add_f32_e32 v74, v74, v106
	v_add_f32_e32 v58, v58, v90
	v_add_f32_e32 v75, v75, v107
	v_add_f32_e32 v59, v59, v91
	v_add_f32_e32 v76, v76, v108
	v_add_f32_e32 v60, v60, v92
	v_add_f32_e32 v77, v77, v109
	v_add_f32_e32 v61, v61, v93
	v_add_f32_e32 v78, v78, v110
	v_add_f32_e32 v62, v62, v94
	v_add_f32_e32 v79, v79, v111
	v_add_f32_e32 v63, v63, v95
	v_add_f32_e32 v80, v80, v112
	v_add_f32_e32 v64, v64, v96
	v_add_f32_e32 v81, v81, v113
	v_add_f32_e32 v65, v65, v97
	v_mov_b32_e32 v98, 0xf149f2ca
	v_cndmask_b32_e32 v66, v98, v66, vcc
	v_cndmask_b32_e64 v50, v98, v50, s[8:9]
	v_cndmask_b32_e64 v67, v98, v67, s[42:43]
	v_cndmask_b32_e64 v51, v98, v51, s[10:11]
	v_cndmask_b32_e64 v68, v98, v68, s[44:45]
	v_cndmask_b32_e64 v52, v98, v52, s[12:13]
	v_cndmask_b32_e64 v69, v98, v69, s[46:47]
	v_cndmask_b32_e64 v53, v98, v53, s[14:15]
	v_cndmask_b32_e64 v70, v98, v70, s[48:49]
	v_cndmask_b32_e64 v54, v98, v54, s[16:17]
	v_cndmask_b32_e64 v71, v98, v71, s[50:51]
	v_cndmask_b32_e64 v55, v98, v55, s[18:19]
	v_cndmask_b32_e64 v72, v98, v72, s[52:53]
	v_cndmask_b32_e64 v56, v98, v56, s[24:25]
	v_cndmask_b32_e64 v73, v98, v73, s[54:55]
	v_cndmask_b32_e64 v57, v98, v57, s[86:87]
	v_cndmask_b32_e64 v74, v98, v74, s[30:31]
	v_cndmask_b32_e64 v58, v98, v58, s[56:57]
	v_cndmask_b32_e64 v75, v98, v75, s[34:35]
	v_cndmask_b32_e64 v59, v98, v59, s[58:59]
	v_cndmask_b32_e64 v76, v98, v76, s[96:97]
	v_cndmask_b32_e64 v60, v98, v60, s[60:61]
	v_cndmask_b32_e64 v77, v98, v77, s[76:77]
	v_cndmask_b32_e64 v61, v98, v61, s[62:63]
	v_cndmask_b32_e64 v78, v98, v78, s[28:29]
	v_cndmask_b32_e64 v62, v98, v62, s[64:65]
	v_cndmask_b32_e64 v79, v98, v79, s[94:95]
	v_cndmask_b32_e64 v63, v98, v63, s[66:67]
	v_cndmask_b32_e64 v80, v98, v80, s[92:93]
	v_cndmask_b32_e64 v64, v98, v64, s[68:69]
	v_cndmask_b32_e64 v81, v98, v81, s[88:89]
	v_cndmask_b32_e64 v65, v98, v65, s[70:71]

; template <int KW, int DV, bool NA> ...
;     ...
;         for (int d0 = 0; d0 < 4; ++d0) {
;             const bf16x8 a0 = *(const bf16x8*)(Kt + q32 * KSTR + (kcoff + 16 * d0 + 8 * hi) * 2);
;             const bf16x8 a1 = *(const bf16x8*)(Kt + (32 + q32) * KSTR + (kcoff + 16 * d0 + 8 * hi) * 2);
;             if (d0 == 0) { p0 = __builtin_amdgcn_mfma_f32_32x32x16_bf16(a0, qf[0], negm, 0, 0, 0); p1 = __builtin_amdgcn_mfma_f32_32x32x16_bf16(a1, qf[0], negm, 0, 0, 0); }
;             else { p0 = __builtin_amdgcn_mfma_f32_32x32x16_bf16(a0, qf[d0], p0, 0, 0, 0); p1 = __builtin_amdgcn_mfma_f32_32x32x16_bf16(a1, qf[d0], p1, 0, 0, 0); }
;         }
;         if (NA && i < n1) {
;             const int kr = na_row0 + i, dr = kr - na_r + 7;
;             const int cs = min(max(na_c - 8, 0), 48);
;             const float* rb = rpbs + dr * 31 - na_c + 15;
; #pragma unroll
;             for (int r = 0; r < 16; ++r) {
;                 const int kc0 = (r & 3) + 8 * (r >> 2) + 4 * hi, kc1 = kc0 + 32;
;                 const bool ok0 = (kc0 >= cs) && (kc0 < cs + 16), ok1 = (kc1 >= cs) && (kc1 < cs + 16);
;                 p0[r] = ok0 ? p0[r] + rb[kc0] : -1e30f;
;                 p1[r] = ok1 ? p1[r] + rb[kc1] : -1e30f;
;             }
;         }
.LBB0_509:
	s_or_b64 exec, exec, s[72:73]
	v_cmp_ge_i32_e64 s[82:83], s6, v163
	v_cmp_lt_i32_e64 s[0:1], s6, v163
	s_and_saveexec_b64 s[26:27], s[0:1]
	v_cmp_ge_i32_e64 s[72:73], s6, v164
	v_cmp_lt_i32_e64 s[74:75], s6, v165
	s_and_b64 s[6:7], s[72:73], s[74:75]
	s_andn2_b64 s[36:37], s[82:83], exec
	s_and_b64 s[6:7], s[6:7], exec
	s_or_b64 s[82:83], s[36:37], s[6:7]
	s_or_b64 exec, exec, s[26:27]
	s_mov_b64 s[74:75], s[22:23]
	s_and_saveexec_b64 s[72:73], s[82:83]
	s_cbranch_execz .LBB0_424
	s_movk_i32 s6, 0x5400
	v_mul_lo_u32 v0, v168, s6
	v_add_u32_e32 v0, 0, v0
	v_add3_u32 v86, v0, v166, v167
	ds_read_b128 v[50:53], v86
	ds_read_b128 v[82:85], v86 offset:4608
	ds_read_b128 v[88:91], v86 offset:32
	ds_read_b128 v[92:95], v86 offset:4640
	ds_read_b128 v[96:99], v86 offset:64
	ds_read_b128 v[100:103], v86 offset:4672
	ds_read_b128 v[104:107], v86 offset:96
	ds_read_b128 v[108:111], v86 offset:4704
	s_waitcnt lgkmcnt(7)
	v_mfma_f32_32x32x16_bf16 v[66:81], v[50:53], v[114:117], v[34:49]
	s_waitcnt lgkmcnt(6)
	v_mfma_f32_32x32x16_bf16 v[50:65], v[82:85], v[114:117], v[34:49]
	s_waitcnt lgkmcnt(5)
	v_mfma_f32_32x32x16_bf16 v[66:81], v[88:91], v[118:121], v[66:81]
	s_waitcnt lgkmcnt(4)
	v_mfma_f32_32x32x16_bf16 v[50:65], v[92:95], v[118:121], v[50:65]
	s_waitcnt lgkmcnt(3)
	v_mfma_f32_32x32x16_bf16 v[66:81], v[96:99], v[122:125], v[66:81]
	s_waitcnt lgkmcnt(2)
	v_mfma_f32_32x32x16_bf16 v[50:65], v[100:103], v[122:125], v[50:65]
	s_waitcnt lgkmcnt(1)
	v_mfma_f32_32x32x16_bf16 v[66:81], v[104:107], v[126:129], v[66:81]
	s_waitcnt lgkmcnt(0)
	v_mfma_f32_32x32x16_bf16 v[50:65], v[108:111], v[126:129], v[50:65]
	s_and_saveexec_b64 s[74:75], s[0:1]
	s_cbranch_execz .LBB0_578
	ds_read_b32 v98, v172 offset:124
	ds_read_b32 v82, v172 offset:252
	ds_read_b32 v99, v172 offset:128
	ds_read_b32 v83, v172 offset:256
	ds_read_b32 v100, v172 offset:132
	ds_read_b32 v84, v172 offset:260
	ds_read_b32 v101, v172 offset:136
	ds_read_b32 v85, v172 offset:264
	ds_read_b32 v102, v172 offset:156
	ds_read_b32 v86, v172 offset:284
	ds_read_b32 v103, v172 offset:160
	ds_read_b32 v87, v172 offset:288
	ds_read_b32 v104, v172 offset:164
	ds_read_b32 v88, v172 offset:292
	ds_read_b32 v105, v172 offset:168
	ds_read_b32 v89, v172 offset:296
	ds_read_b32 v106, v172 offset:188
	ds_read_b32 v90, v172 offset:316
	ds_read_b32 v107, v172 offset:192
	ds_read_b32 v91, v172 offset:320
	ds_read_b32 v108, v172 offset:196
	ds_read_b32 v92, v172 offset:324
	ds_read_b32 v109, v172 offset:200
	ds_read_b32 v93, v172 offset:328
	ds_read_b32 v110, v172 offset:220
	ds_read_b32 v94, v172 offset:348
	ds_read_b32 v111, v172 offset:224
	ds_read_b32 v95, v172 offset:352
	ds_read_b32 v112, v172 offset:228
	ds_read_b32 v96, v172 offset:356
	ds_read_b32 v113, v172 offset:232
	ds_read_b32 v97, v172 offset:360
	s_waitcnt lgkmcnt(0)
	v_add_f32_e32 v66, v66, v98
	v_add_f32_e32 v50, v50, v82
	v_add_f32_e32 v67, v67, v99
	v_add_f32_e32 v51, v51, v83
	v_add_f32_e32 v68, v68, v100
	v_add_f32_e32 v52, v52, v84
	v_add_f32_e32 v69, v69, v101
	v_add_f32_e32 v53, v53, v85
	v_add_f32_e32 v70, v70, v102
	v_add_f32_e32 v54, v54, v86
	v_add_f32_e32 v71, v71, v103
	v_add_f32_e32 v55, v55, v87
	v_add_f32_e32 v72, v72, v104
	v_add_f32_e32 v56, v56, v88
	v_add_f32_e32 v73, v73, v105
	v_add_f32_e32 v57, v57, v89
	v_add_f32_e32 v74, v74, v106
	v_add_f32_e32 v58, v58, v90
	v_add_f32_e32 v75, v75, v107
	v_add_f32_e32 v59, v59, v91
	v_add_f32_e32 v76, v76, v108
	v_add_f32_e32 v60, v60, v92
	v_add_f32_e32 v77, v77, v109
	v_add_f32_e32 v61, v61, v93
	v_add_f32_e32 v78, v78, v110
	v_add_f32_e32 v62, v62, v94
	v_add_f32_e32 v79, v79, v111
	v_add_f32_e32 v63, v63, v95
	v_add_f32_e32 v80, v80, v112
	v_add_f32_e32 v64, v64, v96
	v_add_f32_e32 v81, v81, v113
	v_add_f32_e32 v65, v65, v97
	v_mov_b32_e32 v98, 0xf149f2ca
	v_cndmask_b32_e32 v66, v98, v66, vcc
	v_cndmask_b32_e64 v50, v98, v50, s[8:9]
	v_cndmask_b32_e64 v67, v98, v67, s[42:43]
	v_cndmask_b32_e64 v51, v98, v51, s[10:11]
	v_cndmask_b32_e64 v68, v98, v68, s[44:45]
	v_cndmask_b32_e64 v52, v98, v52, s[12:13]
	v_cndmask_b32_e64 v69, v98, v69, s[46:47]
	v_cndmask_b32_e64 v53, v98, v53, s[14:15]
	v_cndmask_b32_e64 v70, v98, v70, s[48:49]
	v_cndmask_b32_e64 v54, v98, v54, s[16:17]
	v_cndmask_b32_e64 v71, v98, v71, s[50:51]
	v_cndmask_b32_e64 v55, v98, v55, s[18:19]
	v_cndmask_b32_e64 v72, v98, v72, s[52:53]
	v_cndmask_b32_e64 v56, v98, v56, s[24:25]
	v_cndmask_b32_e64 v73, v98, v73, s[54:55]
	v_cndmask_b32_e64 v57, v98, v57, s[86:87]
	v_cndmask_b32_e64 v74, v98, v74, s[30:31]
	v_cndmask_b32_e64 v58, v98, v58, s[56:57]
	v_cndmask_b32_e64 v75, v98, v75, s[34:35]
	v_cndmask_b32_e64 v59, v98, v59, s[58:59]
	v_cndmask_b32_e64 v76, v98, v76, s[96:97]
	v_cndmask_b32_e64 v60, v98, v60, s[60:61]
	v_cndmask_b32_e64 v77, v98, v77, s[76:77]
	v_cndmask_b32_e64 v61, v98, v61, s[62:63]
	v_cndmask_b32_e64 v78, v98, v78, s[28:29]
	v_cndmask_b32_e64 v62, v98, v62, s[64:65]
	v_cndmask_b32_e64 v79, v98, v79, s[94:95]
	v_cndmask_b32_e64 v63, v98, v63, s[66:67]
	v_cndmask_b32_e64 v80, v98, v80, s[92:93]
	v_cndmask_b32_e64 v64, v98, v64, s[68:69]
	v_cndmask_b32_e64 v81, v98, v81, s[88:89]
	v_cndmask_b32_e64 v65, v98, v65, s[70:71]

; __device__ __forceinline__ float bf2f(unsigned u) { return __uint_as_float(u << 16); }
; __device__ __forceinline__ unsigned pk2(float lo, float hi) { f32x2 v = {lo, hi}; hbf16x2 b = __builtin_convertvector(v, hbf16x2); return __builtin_bit_cast(unsigned, b); }
; __device__ __forceinline__ void na_unit(const Params& p, int l, int b, int h, int rb4, bool ctxq, unsigned char* lds) {
;     ...
;     const float il = 1.f / lsum;
; #pragma unroll
;     for (int d = 0; d < 2; ++d)
; #pragma unroll
;         for (int g = 0; g < 4; ++g) {
;             const int dd = 32 * d + 8 * g + 4 * hi;
;             bf16_t* gp = gout + qrow * 512 + h * 64 + dd;
;             const u32x2 gw = *(const u32x2*)gp;
;             const float v0 = o[d][4 * g + 0] * il * bf2f(gw.x & 0xffffu), v1 = o[d][4 * g + 1] * il * bf2f(gw.x >> 16);
;             const float v2 = o[d][4 * g + 2] * il * bf2f(gw.y & 0xffffu), v3 = o[d][4 * g + 3] * il * bf2f(gw.y >> 16);
;             u32x2 ow; ow.x = pk2(v0, v1); ow.y = pk2(v2, v3); *(u32x2*)gp = ow;
;         }
.LBB0_587:
	s_or_b64 exec, exec, s[6:7]
	v_mov_b32_e32 v0, v171
	s_nop 1
	v_permlane32_swap_b32_e32 v171, v0
	v_add_f32_e32 v0, v171, v0
	v_div_scale_f32 v34, s[0:1], v0, v0, 1.0
	v_rcp_f32_e32 v35, v34
	s_nop 0
	v_fma_f32 v36, -v34, v35, 1.0
	v_fmac_f32_e32 v35, v36, v35
	v_div_scale_f32 v36, vcc, 1.0, v0, 1.0
	v_mul_f32_e32 v37, v36, v35
	v_fma_f32 v38, -v34, v37, v36
	v_fmac_f32_e32 v37, v38, v35
	v_fma_f32 v34, -v34, v37, v36
	v_div_fmas_f32 v34, v34, v35, v37
	v_lshlrev_b64 v[36:37], 10, v[146:147]
	v_div_fixup_f32 v34, v34, v0, 1.0
	v_lshl_add_u64 v[36:37], s[50:51], 0, v[36:37]
	v_lshlrev_b32_e32 v0, 3, v149
	v_lshl_add_u64 v[36:37], v[36:37], 0, v[0:1]
	global_load_dwordx2 v[50:51], v[36:37],  off
	global_load_dwordx2 v[52:53], v[36:37],  off offset:16
	global_load_dwordx2 v[54:55], v[36:37],  off offset:32
	global_load_dwordx2 v[56:57], v[36:37],  off offset:48
	global_load_dwordx2 v[58:59], v[36:37],  off offset:64
	global_load_dwordx2 v[60:61], v[36:37],  off offset:80
	global_load_dwordx2 v[62:63], v[36:37],  off offset:96
	global_load_dwordx2 v[64:65], v[36:37],  off offset:112
	v_pk_mul_f32 v[2:3], v[2:3], v[34:35] op_sel_hi:[1,0]
	v_pk_mul_f32 v[4:5], v[4:5], v[34:35] op_sel_hi:[1,0]
	s_waitcnt vmcnt(0)
	v_lshlrev_b32_e32 v40, 16, v50
	v_and_b32_e32 v41, 0xffff0000, v50
	v_lshlrev_b32_e32 v38, 16, v51
	v_and_b32_e32 v39, 0xffff0000, v51
	v_pk_mul_f32 v[2:3], v[2:3], v[40:41]
	v_pk_mul_f32 v[4:5], v[4:5], v[38:39]
	v_cvt_pk_bf16_f32 v2, v2, v3
	v_cvt_pk_bf16_f32 v3, v4, v5
	global_store_dwordx2 v[36:37], v[2:3],  off
	v_pk_mul_f32 v[4:5], v[6:7], v[34:35] op_sel_hi:[1,0]
	v_lshlrev_b32_e32 v6, 16, v52
	v_and_b32_e32 v7, 0xffff0000, v52
	v_pk_mul_f32 v[4:5], v[4:5], v[6:7]
	v_pk_mul_f32 v[6:7], v[8:9], v[34:35] op_sel_hi:[1,0]
	v_lshlrev_b32_e32 v2, 16, v53
	v_and_b32_e32 v3, 0xffff0000, v53
	v_pk_mul_f32 v[2:3], v[6:7], v[2:3]
	v_cvt_pk_bf16_f32 v4, v4, v5
	v_cvt_pk_bf16_f32 v5, v2, v3
	v_lshlrev_b32_e32 v6, 16, v54
	global_store_dwordx2 v[36:37], v[4:5],  off offset:16
	v_pk_mul_f32 v[4:5], v[10:11], v[34:35] op_sel_hi:[1,0]
	v_and_b32_e32 v7, 0xffff0000, v54
	v_pk_mul_f32 v[4:5], v[4:5], v[6:7]
	v_pk_mul_f32 v[6:7], v[12:13], v[34:35] op_sel_hi:[1,0]
	v_lshlrev_b32_e32 v2, 16, v55
	v_and_b32_e32 v3, 0xffff0000, v55
	v_pk_mul_f32 v[2:3], v[6:7], v[2:3]
	v_cvt_pk_bf16_f32 v4, v4, v5
	v_cvt_pk_bf16_f32 v5, v2, v3
	v_lshlrev_b32_e32 v6, 16, v56
	global_store_dwordx2 v[36:37], v[4:5],  off offset:32
	v_pk_mul_f32 v[4:5], v[14:15], v[34:35] op_sel_hi:[1,0]
	v_and_b32_e32 v7, 0xffff0000, v56
	v_pk_mul_f32 v[4:5], v[4:5], v[6:7]
	v_pk_mul_f32 v[6:7], v[16:17], v[34:35] op_sel_hi:[1,0]
	v_lshlrev_b32_e32 v2, 16, v57
	v_and_b32_e32 v3, 0xffff0000, v57
	v_pk_mul_f32 v[2:3], v[6:7], v[2:3]
	v_cvt_pk_bf16_f32 v4, v4, v5
	v_cvt_pk_bf16_f32 v5, v2, v3
	v_lshlrev_b32_e32 v6, 16, v58
	global_store_dwordx2 v[36:37], v[4:5],  off offset:48
	v_pk_mul_f32 v[4:5], v[18:19], v[34:35] op_sel_hi:[1,0]
	v_and_b32_e32 v7, 0xffff0000, v58
	v_pk_mul_f32 v[4:5], v[4:5], v[6:7]
	v_pk_mul_f32 v[6:7], v[20:21], v[34:35] op_sel_hi:[1,0]
	v_lshlrev_b32_e32 v2, 16, v59
	v_and_b32_e32 v3, 0xffff0000, v59
	v_pk_mul_f32 v[2:3], v[6:7], v[2:3]
	v_cvt_pk_bf16_f32 v4, v4, v5
	v_cvt_pk_bf16_f32 v5, v2, v3
	v_lshlrev_b32_e32 v6, 16, v60
	global_store_dwordx2 v[36:37], v[4:5],  off offset:64
	v_pk_mul_f32 v[4:5], v[22:23], v[34:35] op_sel_hi:[1,0]
	v_and_b32_e32 v7, 0xffff0000, v60
	v_pk_mul_f32 v[4:5], v[4:5], v[6:7]
	v_pk_mul_f32 v[6:7], v[24:25], v[34:35] op_sel_hi:[1,0]
	v_lshlrev_b32_e32 v2, 16, v61
	v_and_b32_e32 v3, 0xffff0000, v61
	v_pk_mul_f32 v[2:3], v[6:7], v[2:3]
	v_cvt_pk_bf16_f32 v4, v4, v5
	v_cvt_pk_bf16_f32 v5, v2, v3
	v_lshlrev_b32_e32 v6, 16, v62
	global_store_dwordx2 v[36:37], v[4:5],  off offset:80
	v_pk_mul_f32 v[4:5], v[26:27], v[34:35] op_sel_hi:[1,0]
	v_and_b32_e32 v7, 0xffff0000, v62
	v_pk_mul_f32 v[4:5], v[4:5], v[6:7]
	v_pk_mul_f32 v[6:7], v[28:29], v[34:35] op_sel_hi:[1,0]
	v_lshlrev_b32_e32 v2, 16, v63
	v_and_b32_e32 v3, 0xffff0000, v63
	v_pk_mul_f32 v[2:3], v[6:7], v[2:3]
	v_cvt_pk_bf16_f32 v4, v4, v5
	v_cvt_pk_bf16_f32 v5, v2, v3
	v_lshlrev_b32_e32 v6, 16, v64
	global_store_dwordx2 v[36:37], v[4:5],  off offset:96
	v_pk_mul_f32 v[4:5], v[30:31], v[34:35] op_sel_hi:[1,0]
	v_and_b32_e32 v7, 0xffff0000, v64
	v_pk_mul_f32 v[4:5], v[4:5], v[6:7]
	v_pk_mul_f32 v[6:7], v[32:33], v[34:35] op_sel_hi:[1,0]
	v_lshlrev_b32_e32 v2, 16, v65
	v_and_b32_e32 v3, 0xffff0000, v65
	v_pk_mul_f32 v[2:3], v[6:7], v[2:3]
	v_cvt_pk_bf16_f32 v4, v4, v5
	v_cvt_pk_bf16_f32 v5, v2, v3
	global_store_dwordx2 v[36:37], v[4:5],  off offset:112
	s_barrier

; __device__ __forceinline__ float xor32_sum(float x) { auto rr = __builtin_amdgcn_permlane32_swap(__float_as_uint(x), __float_as_uint(x), false, false); return __uint_as_float(rr[0]) + __uint_as_float(rr[1]); }
; __device__ __forceinline__ float wave_sum(float v) { v = sum8(v); v += dpp_rmir(v); v = xor16_sum(v); return xor32_sum(v); }
; __device__ __forceinline__ void diff_unit(const Params& p, int l, int b, int h, size_t qrow0, int tile_lo, unsigned char* lds) {
;     ...
;     if (m == 0) {
;         float lam;
;         { const float a = p.in[I_LAMQ][(l * 2 + 0) * 64 + lane] * p.in[I_LAMK][(l * 2 + 0) * 64 + lane], c = p.in[I_LAMQ][(l * 2 + 1) * 64 + lane] * p.in[I_LAMK][(l * 2 + 1) * 64 + lane];
;           lam = __expf(wave_sum(a)) - __expf(wave_sum(c)); }
;         float lf = (float)l; asm volatile("" : "+v"(lf));
;         const float li = 0.8f - 0.6f * __expf(-0.3f * lf); lam += li;
;         float ss = 0.f;
; #pragma unroll
;         for (int d = 0; d < 4; ++d)
; #pragma unroll
;             for (int r = 0; r < 16; ++r) { const float v = o[d][r] * il - lam * x1[(32 * d + (r & 3) + 8 * (r >> 2) + 4 * hi) * 32 + q32]; o[d][r] = v; ss += v * v; }
;         ss = xor32_sum(ss);
;         const float rn = rsqrtf(ss * (1.f / 128.f) + 1e-5f) * (1.f - li);
.LBB0_608:
	s_or_b64 exec, exec, s[4:5]
	s_waitcnt lgkmcnt(0)
	s_barrier
	s_and_saveexec_b64 s[0:1], vcc
	s_cbranch_execz .LBB0_359
	v_or_b32_e32 v66, s30, v163
	v_ashrrev_i32_e32 v67, 31, v66
	v_readlane_b32 s4, v253, 58
	v_lshlrev_b64 v[66:67], 2, v[66:67]
	v_readlane_b32 s12, v254, 2
	v_readlane_b32 s13, v254, 3
	v_readlane_b32 s14, v254, 4
	v_readlane_b32 s15, v254, 5
	v_lshl_add_u64 v[70:71], s[12:13], 0, v[66:67]
	v_mov_b32_e32 v83, v182
	v_lshl_add_u64 v[66:67], s[14:15], 0, v[66:67]
	global_load_dword v72, v[70:71], off
	global_load_dword v73, v[70:71], off offset:256
	global_load_dword v79, v[66:67], off
	global_load_dword v82, v[66:67], off offset:256
	v_lshlrev_b64 v[66:67], 10, v[164:165]
	v_lshlrev_b32_e32 v0, 3, v183
	v_lshl_add_u64 v[66:67], s[58:59], 0, v[66:67]
	v_add_u32_e32 v74, 0x400, v68
	v_add_u32_e32 v84, 0x800, v68
	v_add_u32_e32 v96, 0x1000, v68
	v_add_u32_e32 v100, 0x1400, v68
	v_add_u32_e32 v104, 0x1800, v68
	v_add_u32_e32 v108, 0x1c00, v68
	v_add_u32_e32 v112, 0x2000, v68
	v_add_u32_e32 v116, 0x2400, v68
	v_add_u32_e32 v120, 0x2800, v68
	v_add_u32_e32 v124, 0x2c00, v68
	v_add_u32_e32 v128, 0x3000, v68
	s_waitcnt vmcnt(7)
	v_add_u32_e32 v132, 0x3400, v68
	s_waitcnt vmcnt(6)
	v_add_u32_e32 v136, 0x3800, v68
	v_lshl_add_u64 v[66:67], v[66:67], 0, v[0:1]
	v_add_u32_e32 v85, 0xc00, v68
	s_waitcnt vmcnt(5)
	v_add_u32_e32 v140, 0x3c00, v68
	global_load_dwordx2 v[80:81], v[66:67], off
	ds_read2_b32 v[70:71], v68 offset1:32
	ds_read2_b32 v[68:69], v68 offset0:64 offset1:96
	ds_read2_b32 v[76:77], v74 offset1:32
	ds_read2_b32 v[74:75], v74 offset0:64 offset1:96
	ds_read2_b32 v[86:87], v84 offset1:32
	ds_read2_b32 v[88:89], v84 offset0:64 offset1:96
	ds_read2_b32 v[90:91], v85 offset1:32
	ds_read2_b32 v[92:93], v85 offset0:64 offset1:96
	ds_read2_b32 v[94:95], v96 offset1:32
	ds_read2_b32 v[96:97], v96 offset0:64 offset1:96
	ds_read2_b32 v[98:99], v100 offset1:32
	ds_read2_b32 v[100:101], v100 offset0:64 offset1:96
	ds_read2_b32 v[102:103], v104 offset1:32
	ds_read2_b32 v[104:105], v104 offset0:64 offset1:96
	ds_read2_b32 v[106:107], v108 offset1:32
	ds_read2_b32 v[108:109], v108 offset0:64 offset1:96
	ds_read2_b32 v[110:111], v112 offset1:32
	ds_read2_b32 v[112:113], v112 offset0:64 offset1:96
	ds_read2_b32 v[114:115], v116 offset1:32
	ds_read2_b32 v[116:117], v116 offset0:64 offset1:96
	ds_read2_b32 v[118:119], v120 offset1:32
	ds_read2_b32 v[120:121], v120 offset0:64 offset1:96
	ds_read2_b32 v[122:123], v124 offset1:32
	ds_read2_b32 v[124:125], v124 offset0:64 offset1:96
	ds_read2_b32 v[126:127], v128 offset1:32
	ds_read2_b32 v[128:129], v128 offset0:64 offset1:96
	ds_read2_b32 v[130:131], v132 offset1:32
	ds_read2_b32 v[132:133], v132 offset0:64 offset1:96
	ds_read2_b32 v[134:135], v136 offset1:32
	ds_read2_b32 v[136:137], v136 offset0:64 offset1:96
	ds_read2_b32 v[138:139], v140 offset1:32
	v_mul_f32_e32 v0, 0xbe99999a, v83
	v_mul_f32_e32 v0, 0x3fb8aa3b, v0
	v_exp_f32_e32 v0, v0
	ds_read2_b32 v[140:141], v140 offset0:64 offset1:96
	s_mov_b32 s2, 0x800000
	v_readlane_b32 s5, v253, 59
	v_readlane_b32 s6, v253, 60
	v_readlane_b32 s7, v253, 61
	v_readlane_b32 s8, v253, 62
	v_readlane_b32 s9, v253, 63
	v_readlane_b32 s10, v254, 0
	v_readlane_b32 s11, v254, 1
	v_readlane_b32 s16, v254, 6
	v_readlane_b32 s17, v254, 7
	v_readlane_b32 s18, v254, 8
	v_readlane_b32 s19, v254, 9
	s_waitcnt vmcnt(2)
	v_mul_f32_e32 v83, v72, v79
	s_waitcnt vmcnt(1)
	v_mul_f32_e32 v84, v73, v82
	v_mov_b32_dpp v83, v83 quad_perm:[1,0,3,2] row_mask:0xf bank_mask:0xf bound_ctrl:1
	v_fmac_f32_e32 v83, v72, v79
	v_mov_b32_dpp v84, v84 quad_perm:[1,0,3,2] row_mask:0xf bank_mask:0xf bound_ctrl:1
	v_fmac_f32_e32 v84, v73, v82
	v_add_f32_dpp v72, v83, v83 quad_perm:[2,3,0,1] row_mask:0xf bank_mask:0xf bound_ctrl:1
	s_waitcnt vmcnt(0)
	v_lshlrev_b32_e32 v148, 16, v80
	v_add_f32_dpp v73, v84, v84 quad_perm:[2,3,0,1] row_mask:0xf bank_mask:0xf bound_ctrl:1
	v_add_f32_dpp v72, v72, v72 row_half_mirror row_mask:0xf bank_mask:0xf bound_ctrl:1
	v_and_b32_e32 v149, 0xffff0000, v80
	v_add_f32_dpp v73, v73, v73 row_half_mirror row_mask:0xf bank_mask:0xf bound_ctrl:1
	v_add_f32_dpp v72, v72, v72 row_mirror row_mask:0xf bank_mask:0xf bound_ctrl:1
	v_mov_b32_e32 v79, v72
	v_add_f32_dpp v73, v73, v73 row_mirror row_mask:0xf bank_mask:0xf bound_ctrl:1
	v_mov_b32_e32 v82, v73
	v_permlane16_swap_b32_e32 v72, v79
	s_nop 0
	v_permlane16_swap_b32_e32 v73, v82
	v_add_f32_e32 v72, v72, v79
	v_add_f32_e32 v73, v73, v82
	v_mov_b32_e32 v79, v72
	v_mov_b32_e32 v82, v73
	s_nop 0
	v_permlane32_swap_b32_e32 v72, v79
	v_permlane32_swap_b32_e32 v73, v82
	v_add_f32_e32 v72, v72, v79
	v_add_f32_e32 v73, v73, v82
	v_mul_f32_e32 v72, 0x3fb8aa3b, v72
	v_mul_f32_e32 v73, 0x3fb8aa3b, v73
	v_exp_f32_e32 v204, v72
	v_exp_f32_e32 v72, v73
	v_mul_f32_e32 v73, 0x3f19999a, v0
	global_load_dwordx4 v[82:85], v162, s[84:85]
	v_pk_add_f32 v[72:73], v[204:205], v[72:73] neg_lo:[0,1] neg_hi:[0,1]
	s_nop 0
	v_pk_add_f32 v[142:143], v[72:73], v[72:73] op_sel:[0,1] op_sel_hi:[0,1]
	v_sub_f32_e32 v79, 1.0, v73
	s_waitcnt lgkmcnt(14)
; __device__ __forceinline__ float xor32_sum(float x) { auto rr = __builtin_amdgcn_permlane32_swap(__float_as_uint(x), __float_as_uint(x), false, false); return __uint_as_float(rr[0]) + __uint_as_float(rr[1]); }
; __device__ __forceinline__ void diff_unit(const Params& p, int l, int b, int h, size_t qrow0, int tile_lo, unsigned char* lds) {
;     ...
;         float ss = 0.f;
; #pragma unroll
;         for (int d = 0; d < 4; ++d)
; #pragma unroll
;             for (int r = 0; r < 16; ++r) { const float v = o[d][r] * il - lam * x1[(32 * d + (r & 3) + 8 * (r >> 2) + 4 * hi) * 32 + q32]; o[d][r] = v; ss += v * v; }
;         ss = xor32_sum(ss);
	v_pk_mul_f32 v[68:69], v[68:69], v[142:143]
	global_load_dwordx2 v[72:73], v[66:67], off offset:16
	v_pk_fma_f32 v[144:145], v[52:53], v[78:79], v[68:69] op_sel_hi:[1,0,1] neg_lo:[0,0,1] neg_hi:[0,0,1]
	v_pk_mul_f32 v[52:53], v[70:71], v[142:143]
	s_nop 0
	v_pk_fma_f32 v[146:147], v[50:51], v[78:79], v[52:53] op_sel_hi:[1,0,1] neg_lo:[0,0,1] neg_hi:[0,0,1]
	v_pk_mul_f32 v[52:53], v[142:143], v[74:75]
	v_mul_f32_e32 v0, v147, v147
	v_pk_fma_f32 v[50:51], v[146:147], v[146:147], v[0:1] op_sel_hi:[1,1,0]
	v_mul_f32_e32 v0, v145, v145
	v_pk_fma_f32 v[50:51], v[144:145], v[144:145], v[50:51]
	v_pk_fma_f32 v[74:75], v[56:57], v[78:79], v[52:53] op_sel_hi:[1,0,1] neg_lo:[0,0,1] neg_hi:[0,0,1]
	v_pk_mul_f32 v[52:53], v[76:77], v[142:143]
	v_pk_add_f32 v[50:51], v[0:1], v[50:51] op_sel_hi:[0,1]
	v_pk_fma_f32 v[76:77], v[54:55], v[78:79], v[52:53] op_sel_hi:[1,0,1] neg_lo:[0,0,1] neg_hi:[0,0,1]
	v_pk_mul_f32 v[52:53], v[142:143], v[88:89]
	v_pk_fma_f32 v[50:51], v[76:77], v[76:77], v[50:51]
	v_mul_f32_e32 v0, v77, v77
	v_pk_add_f32 v[50:51], v[0:1], v[50:51] op_sel_hi:[0,1]
	v_pk_fma_f32 v[50:51], v[74:75], v[74:75], v[50:51]
	v_mul_f32_e32 v0, v75, v75
	v_pk_fma_f32 v[68:69], v[60:61], v[78:79], v[52:53] op_sel_hi:[1,0,1] neg_lo:[0,0,1] neg_hi:[0,0,1]
	v_pk_mul_f32 v[52:53], v[142:143], v[86:87]
	v_pk_add_f32 v[50:51], v[0:1], v[50:51] op_sel_hi:[0,1]
	v_pk_fma_f32 v[70:71], v[58:59], v[78:79], v[52:53] op_sel_hi:[1,0,1] neg_lo:[0,0,1] neg_hi:[0,0,1]
	v_pk_mul_f32 v[52:53], v[142:143], v[92:93]
	v_pk_fma_f32 v[50:51], v[70:71], v[70:71], v[50:51]
	v_mul_f32_e32 v0, v71, v71
	v_pk_add_f32 v[50:51], v[0:1], v[50:51] op_sel_hi:[0,1]
	v_pk_fma_f32 v[50:51], v[68:69], v[68:69], v[50:51]
	v_mul_f32_e32 v0, v69, v69
	v_pk_fma_f32 v[64:65], v[64:65], v[78:79], v[52:53] op_sel_hi:[1,0,1] neg_lo:[0,0,1] neg_hi:[0,0,1]
	v_pk_mul_f32 v[52:53], v[142:143], v[90:91]
	v_pk_add_f32 v[50:51], v[0:1], v[50:51] op_sel_hi:[0,1]
	v_pk_fma_f32 v[62:63], v[62:63], v[78:79], v[52:53] op_sel_hi:[1,0,1] neg_lo:[0,0,1] neg_hi:[0,0,1]
	v_pk_mul_f32 v[52:53], v[142:143], v[96:97]
	v_pk_fma_f32 v[50:51], v[62:63], v[62:63], v[50:51]
	v_mul_f32_e32 v0, v63, v63
	v_pk_add_f32 v[50:51], v[0:1], v[50:51] op_sel_hi:[0,1]
	v_pk_fma_f32 v[50:51], v[64:65], v[64:65], v[50:51]
	v_mul_f32_e32 v0, v65, v65
	v_pk_fma_f32 v[58:59], v[36:37], v[78:79], v[52:53] op_sel_hi:[1,0,1] neg_lo:[0,0,1] neg_hi:[0,0,1]
	v_pk_mul_f32 v[36:37], v[142:143], v[94:95]
	v_pk_add_f32 v[50:51], v[0:1], v[50:51] op_sel_hi:[0,1]
	v_pk_fma_f32 v[60:61], v[34:35], v[78:79], v[36:37] op_sel_hi:[1,0,1] neg_lo:[0,0,1] neg_hi:[0,0,1]
	v_pk_mul_f32 v[36:37], v[142:143], v[100:101]
	v_pk_fma_f32 v[34:35], v[60:61], v[60:61], v[50:51]
	v_mul_f32_e32 v0, v61, v61
	v_pk_add_f32 v[34:35], v[0:1], v[34:35] op_sel_hi:[0,1]
	v_pk_fma_f32 v[34:35], v[58:59], v[58:59], v[34:35]
	v_mul_f32_e32 v0, v59, v59
	v_pk_fma_f32 v[54:55], v[40:41], v[78:79], v[36:37] op_sel_hi:[1,0,1] neg_lo:[0,0,1] neg_hi:[0,0,1]
	v_pk_mul_f32 v[36:37], v[142:143], v[98:99]
	v_pk_add_f32 v[34:35], v[0:1], v[34:35] op_sel_hi:[0,1]
	v_pk_fma_f32 v[56:57], v[38:39], v[78:79], v[36:37] op_sel_hi:[1,0,1] neg_lo:[0,0,1] neg_hi:[0,0,1]
	v_pk_mul_f32 v[36:37], v[142:143], v[104:105]
	v_pk_fma_f32 v[34:35], v[56:57], v[56:57], v[34:35]
	v_mul_f32_e32 v0, v57, v57
	v_pk_add_f32 v[34:35], v[0:1], v[34:35] op_sel_hi:[0,1]
	v_pk_fma_f32 v[34:35], v[54:55], v[54:55], v[34:35]
	v_mul_f32_e32 v0, v55, v55
	v_pk_fma_f32 v[50:51], v[44:45], v[78:79], v[36:37] op_sel_hi:[1,0,1] neg_lo:[0,0,1] neg_hi:[0,0,1]
	v_pk_mul_f32 v[36:37], v[142:143], v[102:103]
	v_pk_add_f32 v[34:35], v[0:1], v[34:35] op_sel_hi:[0,1]
	v_pk_fma_f32 v[52:53], v[42:43], v[78:79], v[36:37] op_sel_hi:[1,0,1] neg_lo:[0,0,1] neg_hi:[0,0,1]
	v_pk_mul_f32 v[36:37], v[142:143], v[108:109]
	v_pk_fma_f32 v[34:35], v[52:53], v[52:53], v[34:35]
	v_mul_f32_e32 v0, v53, v53
	v_pk_add_f32 v[34:35], v[0:1], v[34:35] op_sel_hi:[0,1]
	v_pk_fma_f32 v[34:35], v[50:51], v[50:51], v[34:35]
	v_mul_f32_e32 v0, v51, v51
	v_pk_fma_f32 v[48:49], v[48:49], v[78:79], v[36:37] op_sel_hi:[1,0,1] neg_lo:[0,0,1] neg_hi:[0,0,1]
	v_pk_mul_f32 v[36:37], v[142:143], v[106:107]
	v_pk_add_f32 v[34:35], v[0:1], v[34:35] op_sel_hi:[0,1]
	v_pk_fma_f32 v[46:47], v[46:47], v[78:79], v[36:37] op_sel_hi:[1,0,1] neg_lo:[0,0,1] neg_hi:[0,0,1]
	v_pk_mul_f32 v[36:37], v[142:143], v[112:113]
	v_pk_fma_f32 v[34:35], v[46:47], v[46:47], v[34:35]
	v_mul_f32_e32 v0, v47, v47
	v_pk_add_f32 v[34:35], v[0:1], v[34:35] op_sel_hi:[0,1]
	v_pk_fma_f32 v[34:35], v[48:49], v[48:49], v[34:35]
	v_mul_f32_e32 v0, v49, v49
	v_pk_fma_f32 v[42:43], v[20:21], v[78:79], v[36:37] op_sel_hi:[1,0,1] neg_lo:[0,0,1] neg_hi:[0,0,1]
	v_pk_mul_f32 v[20:21], v[142:143], v[110:111]
	v_pk_add_f32 v[34:35], v[0:1], v[34:35] op_sel_hi:[0,1]
	v_pk_fma_f32 v[44:45], v[18:19], v[78:79], v[20:21] op_sel_hi:[1,0,1] neg_lo:[0,0,1] neg_hi:[0,0,1]
	s_waitcnt lgkmcnt(12)
	v_pk_mul_f32 v[20:21], v[142:143], v[116:117]
	v_pk_fma_f32 v[18:19], v[44:45], v[44:45], v[34:35]
	v_mul_f32_e32 v0, v45, v45
	v_pk_add_f32 v[18:19], v[0:1], v[18:19] op_sel_hi:[0,1]
	v_pk_fma_f32 v[18:19], v[42:43], v[42:43], v[18:19]
	v_mul_f32_e32 v0, v43, v43
	v_pk_fma_f32 v[38:39], v[24:25], v[78:79], v[20:21] op_sel_hi:[1,0,1] neg_lo:[0,0,1] neg_hi:[0,0,1]
	v_pk_mul_f32 v[20:21], v[142:143], v[114:115]
	v_pk_add_f32 v[18:19], v[0:1], v[18:19] op_sel_hi:[0,1]
	v_pk_fma_f32 v[40:41], v[22:23], v[78:79], v[20:21] op_sel_hi:[1,0,1] neg_lo:[0,0,1] neg_hi:[0,0,1]
	s_waitcnt lgkmcnt(10)
; __device__ __forceinline__ float xor32_sum(float x) { auto rr = __builtin_amdgcn_permlane32_swap(__float_as_uint(x), __float_as_uint(x), false, false); return __uint_as_float(rr[0]) + __uint_as_float(rr[1]); }
; __device__ __forceinline__ void diff_unit(const Params& p, int l, int b, int h, size_t qrow0, int tile_lo, unsigned char* lds) {
;     ...
;         float ss = 0.f;
; #pragma unroll
;         for (int d = 0; d < 4; ++d)
; #pragma unroll
;             for (int r = 0; r < 16; ++r) { const float v = o[d][r] * il - lam * x1[(32 * d + (r & 3) + 8 * (r >> 2) + 4 * hi) * 32 + q32]; o[d][r] = v; ss += v * v; }
;         ss = xor32_sum(ss);
;         const float rn = rsqrtf(ss * (1.f / 128.f) + 1e-5f) * (1.f - li);
; #pragma unroll
;         for (int d = 0; d < 4; ++d)
; #pragma unroll
;             for (int g = 0; g < 4; ++g) {
;                 const int dd = 32 * d + 8 * g + 4 * hi;
;                 bf16_t* gp = gout + qrow * 512 + h * 128 + dd;
;                 const u32x2 gw = *(const u32x2*)gp;
;                 const f32x4 sg = *(const f32x4*)(p.in[I_SUBLN] + l * 128 + dd);
	v_pk_mul_f32 v[20:21], v[142:143], v[120:121]
	v_pk_fma_f32 v[18:19], v[40:41], v[40:41], v[18:19]
	v_mul_f32_e32 v0, v41, v41
	v_pk_add_f32 v[18:19], v[0:1], v[18:19] op_sel_hi:[0,1]
	v_pk_fma_f32 v[18:19], v[38:39], v[38:39], v[18:19]
	v_mul_f32_e32 v0, v39, v39
	v_pk_fma_f32 v[34:35], v[28:29], v[78:79], v[20:21] op_sel_hi:[1,0,1] neg_lo:[0,0,1] neg_hi:[0,0,1]
	v_pk_mul_f32 v[20:21], v[142:143], v[118:119]
	v_pk_add_f32 v[18:19], v[0:1], v[18:19] op_sel_hi:[0,1]
	v_pk_fma_f32 v[36:37], v[26:27], v[78:79], v[20:21] op_sel_hi:[1,0,1] neg_lo:[0,0,1] neg_hi:[0,0,1]
	s_waitcnt lgkmcnt(8)
	v_pk_mul_f32 v[20:21], v[142:143], v[124:125]
	v_pk_fma_f32 v[18:19], v[36:37], v[36:37], v[18:19]
	v_mul_f32_e32 v0, v37, v37
	v_pk_add_f32 v[18:19], v[0:1], v[18:19] op_sel_hi:[0,1]
	v_pk_fma_f32 v[18:19], v[34:35], v[34:35], v[18:19]
	v_mul_f32_e32 v0, v35, v35
	v_pk_fma_f32 v[26:27], v[32:33], v[78:79], v[20:21] op_sel_hi:[1,0,1] neg_lo:[0,0,1] neg_hi:[0,0,1]
	v_pk_mul_f32 v[20:21], v[142:143], v[122:123]
	v_pk_add_f32 v[18:19], v[0:1], v[18:19] op_sel_hi:[0,1]
	v_pk_fma_f32 v[28:29], v[30:31], v[78:79], v[20:21] op_sel_hi:[1,0,1] neg_lo:[0,0,1] neg_hi:[0,0,1]
	s_waitcnt lgkmcnt(6)
	v_pk_mul_f32 v[20:21], v[142:143], v[128:129]
	v_pk_fma_f32 v[18:19], v[28:29], v[28:29], v[18:19]
	v_mul_f32_e32 v0, v29, v29
	v_pk_add_f32 v[18:19], v[0:1], v[18:19] op_sel_hi:[0,1]
	v_pk_fma_f32 v[18:19], v[26:27], v[26:27], v[18:19]
	v_mul_f32_e32 v0, v27, v27
	v_pk_fma_f32 v[22:23], v[4:5], v[78:79], v[20:21] op_sel_hi:[1,0,1] neg_lo:[0,0,1] neg_hi:[0,0,1]
	v_pk_mul_f32 v[4:5], v[142:143], v[126:127]
	v_pk_add_f32 v[18:19], v[0:1], v[18:19] op_sel_hi:[0,1]
	v_pk_fma_f32 v[24:25], v[2:3], v[78:79], v[4:5] op_sel_hi:[1,0,1] neg_lo:[0,0,1] neg_hi:[0,0,1]
	s_waitcnt lgkmcnt(4)
	v_pk_mul_f32 v[4:5], v[142:143], v[132:133]
	v_pk_fma_f32 v[2:3], v[24:25], v[24:25], v[18:19]
	v_mul_f32_e32 v0, v25, v25
	v_pk_add_f32 v[2:3], v[0:1], v[2:3] op_sel_hi:[0,1]
	v_pk_fma_f32 v[2:3], v[22:23], v[22:23], v[2:3]
	v_mul_f32_e32 v0, v23, v23
	v_pk_fma_f32 v[18:19], v[8:9], v[78:79], v[4:5] op_sel_hi:[1,0,1] neg_lo:[0,0,1] neg_hi:[0,0,1]
	v_pk_mul_f32 v[4:5], v[142:143], v[130:131]
	v_pk_add_f32 v[2:3], v[0:1], v[2:3] op_sel_hi:[0,1]
	v_pk_fma_f32 v[20:21], v[6:7], v[78:79], v[4:5] op_sel_hi:[1,0,1] neg_lo:[0,0,1] neg_hi:[0,0,1]
	s_waitcnt lgkmcnt(2)
	v_pk_mul_f32 v[4:5], v[142:143], v[136:137]
	v_pk_fma_f32 v[2:3], v[20:21], v[20:21], v[2:3]
	v_mul_f32_e32 v0, v21, v21
	v_pk_add_f32 v[2:3], v[0:1], v[2:3] op_sel_hi:[0,1]
	v_pk_fma_f32 v[2:3], v[18:19], v[18:19], v[2:3]
	v_mul_f32_e32 v0, v19, v19
	v_pk_fma_f32 v[12:13], v[12:13], v[78:79], v[4:5] op_sel_hi:[1,0,1] neg_lo:[0,0,1] neg_hi:[0,0,1]
	v_pk_mul_f32 v[4:5], v[142:143], v[134:135]
	v_pk_add_f32 v[2:3], v[0:1], v[2:3] op_sel_hi:[0,1]
	v_pk_fma_f32 v[10:11], v[10:11], v[78:79], v[4:5] op_sel_hi:[1,0,1] neg_lo:[0,0,1] neg_hi:[0,0,1]
	s_waitcnt lgkmcnt(0)
	v_pk_mul_f32 v[4:5], v[142:143], v[140:141]
	v_pk_fma_f32 v[2:3], v[10:11], v[10:11], v[2:3]
	v_mul_f32_e32 v0, v11, v11
	v_pk_add_f32 v[2:3], v[0:1], v[2:3] op_sel_hi:[0,1]
	v_pk_fma_f32 v[2:3], v[12:13], v[12:13], v[2:3]
	v_mul_f32_e32 v0, v13, v13
	v_pk_fma_f32 v[6:7], v[16:17], v[78:79], v[4:5] op_sel_hi:[1,0,1] neg_lo:[0,0,1] neg_hi:[0,0,1]
	v_pk_mul_f32 v[4:5], v[142:143], v[138:139]
	v_pk_add_f32 v[2:3], v[0:1], v[2:3] op_sel_hi:[0,1]
	v_pk_fma_f32 v[8:9], v[14:15], v[78:79], v[4:5] op_sel_hi:[1,0,1] neg_lo:[0,0,1] neg_hi:[0,0,1]
	s_waitcnt vmcnt(0)
	global_load_dwordx4 v[86:89], v162, s[84:85] offset:32
	global_load_dwordx2 v[90:91], v[66:67],  off offset:32
	global_load_dwordx4 v[92:95], v162, s[84:85] offset:64
	global_load_dwordx2 v[96:97], v[66:67],  off offset:48
	global_load_dwordx4 v[98:101], v162, s[84:85] offset:96
	global_load_dwordx2 v[102:103], v[66:67],  off offset:64
	global_load_dwordx4 v[104:107], v162, s[84:85] offset:128
	global_load_dwordx2 v[108:109], v[66:67],  off offset:80
	global_load_dwordx4 v[110:113], v162, s[84:85] offset:160
	global_load_dwordx2 v[114:115], v[66:67],  off offset:96
	global_load_dwordx4 v[116:119], v162, s[84:85] offset:192
	global_load_dwordx2 v[120:121], v[66:67],  off offset:112
	global_load_dwordx4 v[122:125], v162, s[84:85] offset:224
	global_load_dwordx2 v[126:127], v[66:67],  off offset:128
	global_load_dwordx4 v[128:131], v162, s[84:85] offset:256
	global_load_dwordx2 v[132:133], v[66:67],  off offset:144
	global_load_dwordx4 v[134:137], v162, s[84:85] offset:288
	global_load_dwordx2 v[138:139], v[66:67],  off offset:160
	global_load_dwordx4 v[140:143], v162, s[84:85] offset:320
	global_load_dwordx2 v[150:151], v[66:67],  off offset:176
	global_load_dwordx4 v[152:155], v162, s[84:85] offset:352
	global_load_dwordx2 v[156:157], v[66:67],  off offset:192
	global_load_dwordx4 v[158:161], v162, s[84:85] offset:384
	global_load_dwordx2 v[164:165], v[66:67],  off offset:208
	global_load_dwordx4 v[166:169], v162, s[84:85] offset:416
	global_load_dwordx2 v[170:171], v[66:67],  off offset:224
	global_load_dwordx4 v[172:175], v162, s[84:85] offset:448
	global_load_dwordx2 v[176:177], v[66:67],  off offset:240
	global_load_dwordx4 v[178:181], v162, s[84:85] offset:480
	v_lshlrev_b32_e32 v16, 16, v72
	v_pk_fma_f32 v[2:3], v[8:9], v[8:9], v[2:3]
	v_mul_f32_e32 v0, v9, v9
	v_pk_add_f32 v[2:3], v[0:1], v[2:3] op_sel_hi:[0,1]
	v_pk_fma_f32 v[2:3], v[6:7], v[6:7], v[2:3]
	v_mul_f32_e32 v0, v7, v7
	v_pk_add_f32 v[2:3], v[0:1], v[2:3] op_sel_hi:[0,1]
	v_mov_b32_e32 v0, v2
	s_nop 1
	v_permlane32_swap_b32_e32 v2, v0
	v_add_f32_e32 v0, v2, v0
	v_fmamk_f32 v0, v0, 0x3c000000, v233
	v_mul_f32_e32 v2, 0x4b800000, v0
	v_cmp_gt_f32_e32 vcc, s2, v0
; __device__ __forceinline__ float bf2f(unsigned u) { return __uint_as_float(u << 16); }
; __device__ __forceinline__ unsigned pk2(float lo, float hi) { f32x2 v = {lo, hi}; hbf16x2 b = __builtin_convertvector(v, hbf16x2); return __builtin_bit_cast(unsigned, b); }
; __device__ __forceinline__ void diff_unit(const Params& p, int l, int b, int h, size_t qrow0, int tile_lo, unsigned char* lds) {
;     ...
;         const float rn = rsqrtf(ss * (1.f / 128.f) + 1e-5f) * (1.f - li);
; #pragma unroll
;         for (int d = 0; d < 4; ++d)
; #pragma unroll
;             for (int g = 0; g < 4; ++g) {
;                 const int dd = 32 * d + 8 * g + 4 * hi;
;                 bf16_t* gp = gout + qrow * 512 + h * 128 + dd;
;                 const u32x2 gw = *(const u32x2*)gp;
;                 const f32x4 sg = *(const f32x4*)(p.in[I_SUBLN] + l * 128 + dd);
;                 const float v0 = o[d][4 * g + 0] * rn * sg[0] * bf2f(gw.x & 0xffffu), v1 = o[d][4 * g + 1] * rn * sg[1] * bf2f(gw.x >> 16);
;                 const float v2 = o[d][4 * g + 2] * rn * sg[2] * bf2f(gw.y & 0xffffu), v3 = o[d][4 * g + 3] * rn * sg[3] * bf2f(gw.y >> 16);
;                 u32x2 ow; ow.x = pk2(v0, v1); ow.y = pk2(v2, v3); *(u32x2*)gp = ow;
	v_and_b32_e32 v3, 0xffff0000, v81
	v_and_b32_e32 v17, 0xffff0000, v72
	v_cndmask_b32_e32 v0, v0, v2, vcc
	v_rsq_f32_e32 v0, v0
	v_lshlrev_b32_e32 v2, 16, v81
	v_lshlrev_b32_e32 v30, 16, v73
	v_and_b32_e32 v31, 0xffff0000, v73
	v_mul_f32_e32 v4, 0x45800000, v0
	v_cndmask_b32_e32 v0, v0, v4, vcc
	v_mul_f32_e32 v0, v79, v0
	v_pk_mul_f32 v[4:5], v[146:147], v[0:1] op_sel_hi:[1,0]
	v_pk_mul_f32 v[14:15], v[144:145], v[0:1] op_sel_hi:[1,0]
	v_pk_mul_f32 v[4:5], v[82:83], v[4:5]
	v_pk_mul_f32 v[14:15], v[84:85], v[14:15]
	v_pk_mul_f32 v[4:5], v[4:5], v[148:149]
	v_pk_mul_f32 v[2:3], v[14:15], v[2:3]
	v_cvt_pk_bf16_f32 v4, v4, v5
	v_cvt_pk_bf16_f32 v5, v2, v3
	global_store_dwordx2 v[66:67], v[4:5],  off
	s_nop 0
	v_pk_mul_f32 v[32:33], v[76:77], v[0:1] op_sel_hi:[1,0]
	v_pk_mul_f32 v[68:69], v[68:69], v[0:1] op_sel_hi:[1,0]
	v_pk_mul_f32 v[58:59], v[58:59], v[0:1] op_sel_hi:[1,0]
	v_pk_mul_f32 v[54:55], v[54:55], v[0:1] op_sel_hi:[1,0]
	v_pk_mul_f32 v[50:51], v[50:51], v[0:1] op_sel_hi:[1,0]
	v_pk_mul_f32 v[42:43], v[42:43], v[0:1] op_sel_hi:[1,0]
	v_pk_mul_f32 v[38:39], v[38:39], v[0:1] op_sel_hi:[1,0]
	v_pk_mul_f32 v[34:35], v[34:35], v[0:1] op_sel_hi:[1,0]
	v_pk_mul_f32 v[28:29], v[28:29], v[0:1] op_sel_hi:[1,0]
	v_pk_mul_f32 v[26:27], v[26:27], v[0:1] op_sel_hi:[1,0]
	v_pk_mul_f32 v[24:25], v[24:25], v[0:1] op_sel_hi:[1,0]
	v_pk_mul_f32 v[22:23], v[22:23], v[0:1] op_sel_hi:[1,0]
	v_pk_mul_f32 v[20:21], v[20:21], v[0:1] op_sel_hi:[1,0]
	v_pk_mul_f32 v[18:19], v[18:19], v[0:1] op_sel_hi:[1,0]
	v_pk_mul_f32 v[10:11], v[10:11], v[0:1] op_sel_hi:[1,0]
	v_pk_mul_f32 v[12:13], v[12:13], v[0:1] op_sel_hi:[1,0]
	v_pk_mul_f32 v[8:9], v[8:9], v[0:1] op_sel_hi:[1,0]
	v_pk_mul_f32 v[6:7], v[6:7], v[0:1] op_sel_hi:[1,0]
	s_waitcnt vmcnt(0)
; __device__ __forceinline__ float bf2f(unsigned u) { return __uint_as_float(u << 16); }
; __device__ __forceinline__ unsigned pk2(float lo, float hi) { f32x2 v = {lo, hi}; hbf16x2 b = __builtin_convertvector(v, hbf16x2); return __builtin_bit_cast(unsigned, b); }
; __device__ __forceinline__ void diff_unit(const Params& p, int l, int b, int h, size_t qrow0, int tile_lo, unsigned char* lds) {
;     ...
; #pragma unroll
;         for (int d = 0; d < 4; ++d)
; #pragma unroll
;             for (int g = 0; g < 4; ++g) {
;                 const int dd = 32 * d + 8 * g + 4 * hi;
;                 bf16_t* gp = gout + qrow * 512 + h * 128 + dd;
;                 const u32x2 gw = *(const u32x2*)gp;
;                 const f32x4 sg = *(const f32x4*)(p.in[I_SUBLN] + l * 128 + dd);
;                 const float v0 = o[d][4 * g + 0] * rn * sg[0] * bf2f(gw.x & 0xffffu), v1 = o[d][4 * g + 1] * rn * sg[1] * bf2f(gw.x >> 16);
;                 const float v2 = o[d][4 * g + 2] * rn * sg[2] * bf2f(gw.y & 0xffffu), v3 = o[d][4 * g + 3] * rn * sg[3] * bf2f(gw.y >> 16);
;                 u32x2 ow; ow.x = pk2(v0, v1); ow.y = pk2(v2, v3); *(u32x2*)gp = ow;
;             }
	v_pk_mul_f32 v[2:3], v[86:87], v[32:33]
	s_nop 0
	v_pk_mul_f32 v[2:3], v[2:3], v[16:17]
	v_pk_mul_f32 v[16:17], v[74:75], v[0:1] op_sel_hi:[1,0]
	v_cvt_pk_bf16_f32 v2, v2, v3
	v_pk_mul_f32 v[4:5], v[88:89], v[16:17]
	v_pk_mul_f32 v[32:33], v[70:71], v[0:1] op_sel_hi:[1,0]
	v_pk_mul_f32 v[4:5], v[4:5], v[30:31]
	v_lshlrev_b32_e32 v30, 16, v90
	v_cvt_pk_bf16_f32 v3, v4, v5
	global_store_dwordx2 v[66:67], v[2:3],  off offset:16
	s_nop 0
	v_and_b32_e32 v31, 0xffff0000, v90
	v_lshlrev_b32_e32 v14, 16, v91
	v_and_b32_e32 v15, 0xffff0000, v91
	v_pk_mul_f32 v[2:3], v[92:93], v[32:33]
	v_pk_mul_f32 v[4:5], v[94:95], v[68:69]
	v_pk_mul_f32 v[2:3], v[2:3], v[30:31]
	v_pk_mul_f32 v[4:5], v[4:5], v[14:15]
	v_cvt_pk_bf16_f32 v2, v2, v3
	v_cvt_pk_bf16_f32 v3, v4, v5
	global_store_dwordx2 v[66:67], v[2:3],  off offset:32
	s_nop 0
	v_pk_mul_f32 v[32:33], v[62:63], v[0:1] op_sel_hi:[1,0]
	v_pk_mul_f32 v[62:63], v[64:65], v[0:1] op_sel_hi:[1,0]
	v_lshlrev_b32_e32 v30, 16, v96
	v_and_b32_e32 v31, 0xffff0000, v96
	v_lshlrev_b32_e32 v16, 16, v97
	v_and_b32_e32 v17, 0xffff0000, v97
	v_pk_mul_f32 v[2:3], v[32:33], v[98:99]
	v_pk_mul_f32 v[4:5], v[62:63], v[100:101]
	v_pk_mul_f32 v[2:3], v[2:3], v[30:31]
	v_pk_mul_f32 v[4:5], v[4:5], v[16:17]
	v_cvt_pk_bf16_f32 v2, v2, v3
	v_cvt_pk_bf16_f32 v3, v4, v5
	global_store_dwordx2 v[66:67], v[2:3],  off offset:48
	s_nop 0
	v_pk_mul_f32 v[32:33], v[60:61], v[0:1] op_sel_hi:[1,0]
	v_lshlrev_b32_e32 v30, 16, v102
	v_and_b32_e32 v31, 0xffff0000, v102
	v_lshlrev_b32_e32 v14, 16, v103
	v_and_b32_e32 v15, 0xffff0000, v103
	v_pk_mul_f32 v[2:3], v[32:33], v[104:105]
	v_pk_mul_f32 v[4:5], v[58:59], v[106:107]
	v_pk_mul_f32 v[2:3], v[2:3], v[30:31]
	v_pk_mul_f32 v[4:5], v[4:5], v[14:15]
	v_cvt_pk_bf16_f32 v2, v2, v3
	v_cvt_pk_bf16_f32 v3, v4, v5
	global_store_dwordx2 v[66:67], v[2:3],  off offset:64
	s_nop 0
	v_pk_mul_f32 v[32:33], v[56:57], v[0:1] op_sel_hi:[1,0]
	v_lshlrev_b32_e32 v30, 16, v108
	v_and_b32_e32 v31, 0xffff0000, v108
	v_lshlrev_b32_e32 v16, 16, v109
	v_and_b32_e32 v17, 0xffff0000, v109
	v_pk_mul_f32 v[2:3], v[32:33], v[110:111]
	v_pk_mul_f32 v[4:5], v[54:55], v[112:113]
	v_pk_mul_f32 v[2:3], v[2:3], v[30:31]
	v_pk_mul_f32 v[4:5], v[4:5], v[16:17]
	v_cvt_pk_bf16_f32 v2, v2, v3
	v_cvt_pk_bf16_f32 v3, v4, v5
	global_store_dwordx2 v[66:67], v[2:3],  off offset:80
	s_nop 0
	v_pk_mul_f32 v[32:33], v[52:53], v[0:1] op_sel_hi:[1,0]
	v_lshlrev_b32_e32 v30, 16, v114
	v_and_b32_e32 v31, 0xffff0000, v114
	v_lshlrev_b32_e32 v14, 16, v115
	v_and_b32_e32 v15, 0xffff0000, v115
	v_pk_mul_f32 v[2:3], v[32:33], v[116:117]
	v_pk_mul_f32 v[4:5], v[50:51], v[118:119]
	v_pk_mul_f32 v[2:3], v[2:3], v[30:31]
	v_pk_mul_f32 v[4:5], v[4:5], v[14:15]
	v_cvt_pk_bf16_f32 v2, v2, v3
	v_cvt_pk_bf16_f32 v3, v4, v5
	global_store_dwordx2 v[66:67], v[2:3],  off offset:96
	s_nop 0
	v_pk_mul_f32 v[32:33], v[46:47], v[0:1] op_sel_hi:[1,0]
	v_pk_mul_f32 v[46:47], v[48:49], v[0:1] op_sel_hi:[1,0]
	v_lshlrev_b32_e32 v30, 16, v120
	v_and_b32_e32 v31, 0xffff0000, v120
	v_lshlrev_b32_e32 v16, 16, v121
	v_and_b32_e32 v17, 0xffff0000, v121
	v_pk_mul_f32 v[2:3], v[32:33], v[122:123]
	v_pk_mul_f32 v[4:5], v[46:47], v[124:125]
	v_pk_mul_f32 v[2:3], v[2:3], v[30:31]
	v_pk_mul_f32 v[4:5], v[4:5], v[16:17]
	v_cvt_pk_bf16_f32 v2, v2, v3
	v_cvt_pk_bf16_f32 v3, v4, v5
	global_store_dwordx2 v[66:67], v[2:3],  off offset:112
	s_nop 0
	v_pk_mul_f32 v[32:33], v[44:45], v[0:1] op_sel_hi:[1,0]
	v_lshlrev_b32_e32 v30, 16, v126
	v_and_b32_e32 v31, 0xffff0000, v126
	v_lshlrev_b32_e32 v14, 16, v127
	v_and_b32_e32 v15, 0xffff0000, v127
	v_pk_mul_f32 v[2:3], v[32:33], v[128:129]
	v_pk_mul_f32 v[4:5], v[42:43], v[130:131]
	v_pk_mul_f32 v[2:3], v[2:3], v[30:31]
	v_pk_mul_f32 v[4:5], v[4:5], v[14:15]
	v_cvt_pk_bf16_f32 v2, v2, v3
	v_cvt_pk_bf16_f32 v3, v4, v5
	global_store_dwordx2 v[66:67], v[2:3],  off offset:128
	s_nop 0
	v_pk_mul_f32 v[32:33], v[40:41], v[0:1] op_sel_hi:[1,0]
	v_lshlrev_b32_e32 v30, 16, v132
	v_and_b32_e32 v31, 0xffff0000, v132
	v_lshlrev_b32_e32 v16, 16, v133
	v_and_b32_e32 v17, 0xffff0000, v133
	v_pk_mul_f32 v[2:3], v[32:33], v[134:135]
	v_pk_mul_f32 v[4:5], v[38:39], v[136:137]
	v_pk_mul_f32 v[2:3], v[2:3], v[30:31]
	v_pk_mul_f32 v[4:5], v[4:5], v[16:17]
	v_cvt_pk_bf16_f32 v2, v2, v3
	v_cvt_pk_bf16_f32 v3, v4, v5
	global_store_dwordx2 v[66:67], v[2:3],  off offset:144
	s_nop 0
	v_pk_mul_f32 v[32:33], v[36:37], v[0:1] op_sel_hi:[1,0]
	v_lshlrev_b32_e32 v30, 16, v138
	v_and_b32_e32 v31, 0xffff0000, v138
	v_lshlrev_b32_e32 v14, 16, v139
	v_and_b32_e32 v15, 0xffff0000, v139
	v_pk_mul_f32 v[2:3], v[32:33], v[140:141]
	v_pk_mul_f32 v[4:5], v[34:35], v[142:143]
	v_pk_mul_f32 v[2:3], v[2:3], v[30:31]
	v_pk_mul_f32 v[4:5], v[4:5], v[14:15]
	v_cvt_pk_bf16_f32 v2, v2, v3
	v_cvt_pk_bf16_f32 v3, v4, v5
	global_store_dwordx2 v[66:67], v[2:3],  off offset:160
	s_nop 0
	v_lshlrev_b32_e32 v30, 16, v150
	v_and_b32_e32 v31, 0xffff0000, v150
	v_lshlrev_b32_e32 v16, 16, v151
	v_and_b32_e32 v17, 0xffff0000, v151
	v_pk_mul_f32 v[2:3], v[28:29], v[152:153]
	v_pk_mul_f32 v[4:5], v[26:27], v[154:155]
	v_pk_mul_f32 v[2:3], v[2:3], v[30:31]
	v_pk_mul_f32 v[4:5], v[4:5], v[16:17]
	v_cvt_pk_bf16_f32 v2, v2, v3
	v_cvt_pk_bf16_f32 v3, v4, v5
	global_store_dwordx2 v[66:67], v[2:3],  off offset:176
	s_nop 0
	v_lshlrev_b32_e32 v26, 16, v156
	v_and_b32_e32 v27, 0xffff0000, v156
	v_lshlrev_b32_e32 v14, 16, v157
	v_and_b32_e32 v15, 0xffff0000, v157
	v_pk_mul_f32 v[2:3], v[24:25], v[158:159]
	v_pk_mul_f32 v[4:5], v[22:23], v[160:161]
	v_pk_mul_f32 v[2:3], v[2:3], v[26:27]
	v_pk_mul_f32 v[4:5], v[4:5], v[14:15]
	v_cvt_pk_bf16_f32 v2, v2, v3
	v_cvt_pk_bf16_f32 v3, v4, v5
	global_store_dwordx2 v[66:67], v[2:3],  off offset:192
	s_nop 0
	v_lshlrev_b32_e32 v22, 16, v164
	v_and_b32_e32 v23, 0xffff0000, v164
	v_lshlrev_b32_e32 v16, 16, v165
	v_and_b32_e32 v17, 0xffff0000, v165
	v_pk_mul_f32 v[2:3], v[20:21], v[166:167]
	v_pk_mul_f32 v[4:5], v[18:19], v[168:169]
	v_pk_mul_f32 v[2:3], v[2:3], v[22:23]
	v_pk_mul_f32 v[4:5], v[4:5], v[16:17]
	v_cvt_pk_bf16_f32 v2, v2, v3
	v_cvt_pk_bf16_f32 v3, v4, v5
	global_store_dwordx2 v[66:67], v[2:3],  off offset:208
	s_nop 0
	v_lshlrev_b32_e32 v18, 16, v170
	v_and_b32_e32 v19, 0xffff0000, v170
	v_lshlrev_b32_e32 v14, 16, v171
	v_and_b32_e32 v15, 0xffff0000, v171
	v_pk_mul_f32 v[2:3], v[10:11], v[172:173]
	v_pk_mul_f32 v[4:5], v[12:13], v[174:175]
	v_pk_mul_f32 v[2:3], v[2:3], v[18:19]
	v_pk_mul_f32 v[4:5], v[4:5], v[14:15]
	v_cvt_pk_bf16_f32 v2, v2, v3
	v_cvt_pk_bf16_f32 v3, v4, v5
	global_store_dwordx2 v[66:67], v[2:3],  off offset:224
	v_lshlrev_b32_e32 v10, 16, v176
	v_and_b32_e32 v11, 0xffff0000, v176
	v_lshlrev_b32_e32 v12, 16, v177
	v_and_b32_e32 v13, 0xffff0000, v177
	v_pk_mul_f32 v[2:3], v[8:9], v[178:179]
	v_pk_mul_f32 v[4:5], v[6:7], v[180:181]
	v_pk_mul_f32 v[2:3], v[2:3], v[10:11]
	v_pk_mul_f32 v[4:5], v[4:5], v[12:13]
	v_cvt_pk_bf16_f32 v2, v2, v3
	v_cvt_pk_bf16_f32 v3, v4, v5
	global_store_dwordx2 v[66:67], v[2:3],  off offset:240
	s_branch .LBB0_359
